# leading-half priority held through its first MFMA block of the next unit (reset after second K barrier)
# speedup vs baseline: 1.0037x; 1.0037x over previous
.Lp1b_skip:
	v_mfma_f32_16x16x32_bf16 v[128:131], v[134:137], v[218:221], 0
	v_mfma_f32_16x16x32_bf16 v[128:131], v[138:141], v[226:229], v[128:131]
	s_add_i32 s0, s0, 1
	s_mul_i32 s8, s0, s3
	s_mul_hi_u32 s9, s0, s33
	s_add_i32 s9, s9, s8
	s_mul_i32 s8, s0, s33
	v_mfma_f32_16x16x32_bf16 v[112:115], v[134:137], v[222:225], 0
	v_mfma_f32_16x16x32_bf16 v[112:115], v[138:141], v[230:233], v[112:115]
	s_add_u32 s26, s8, s2
	s_addc_u32 s27, s9, s73
	v_cmp_lt_i64_e64 s[8:9], s[26:27], v[170:171]
	s_ashr_i32 s24, s26, 31
	s_lshr_b32 s24, s24, 29
	v_mfma_f32_16x16x32_bf16 v[96:99], v[134:137], v[234:237], 0
	v_mfma_f32_16x16x32_bf16 v[96:99], v[138:141], v[242:245], v[96:99]
	s_add_i32 s24, s26, s24
	s_ashr_i32 s25, s24, 3
	s_and_b32 s24, s24, -8
	s_sub_i32 s24, s26, s24
	s_cmp_lt_i32 s24, 0
	v_mfma_f32_16x16x32_bf16 v[80:83], v[134:137], v[238:241], 0
	v_mfma_f32_16x16x32_bf16 v[80:83], v[138:141], v[246:249], v[80:83]
	s_movk_i32 s26, 0xb1
	s_cselect_b32 s26, s26, 0xb0
	s_mul_i32 s24, s24, s26
	s_add_i32 s24, s24, s25
	s_mul_hi_i32 s25, s24, 0x2e8ba2e9
	v_mfma_f32_16x16x32_bf16 v[76:79], v[142:145], v[238:241], 0
	v_mfma_f32_16x16x32_bf16 v[76:79], v[146:149], v[246:249], v[76:79]
	s_lshr_b32 s26, s25, 31
	s_ashr_i32 s25, s25, 5
	s_add_i32 s25, s25, s26
	s_lshl_b32 s26, s25, 3
	s_sub_i32 s27, 64, s26
	v_mfma_f32_16x16x32_bf16 v[92:95], v[142:145], v[234:237], 0
	v_mfma_f32_16x16x32_bf16 v[92:95], v[146:149], v[242:245], v[92:95]
	s_min_i32 s27, s27, 8
	s_abs_i32 s28, s27
	v_cvt_f32_u32_e32 v255, s28
	s_sub_i32 s34, 0, s28
	s_mulk_i32 s25, 0xb0
	v_mfma_f32_16x16x32_bf16 v[108:111], v[142:145], v[222:225], 0
	v_mfma_f32_16x16x32_bf16 v[108:111], v[146:149], v[230:233], v[108:111]
	s_sub_i32 s24, s24, s25
	v_rcp_iflag_f32_e32 v255, v255
	s_abs_i32 s25, s24
	s_xor_b32 s29, s24, s27
	s_ashr_i32 s29, s29, 31
	v_mfma_f32_16x16x32_bf16 v[124:127], v[142:145], v[218:221], 0
	v_mfma_f32_16x16x32_bf16 v[124:127], v[146:149], v[226:229], v[124:127]
	v_mul_f32_e32 v255, 0x4f7ffffe, v255
	v_cvt_u32_f32_e32 v255, v255
	s_nop 0
	v_readfirstlane_b32 s35, v255
	s_mul_i32 s34, s34, s35
	v_mfma_f32_16x16x32_bf16 v[120:123], v[150:153], v[218:221], 0
	v_mfma_f32_16x16x32_bf16 v[120:123], v[174:177], v[226:229], v[120:123]
	s_mul_hi_u32 s34, s35, s34
	s_add_i32 s35, s35, s34
	s_mul_hi_u32 s34, s25, s35
	s_mul_i32 s35, s34, s28
	s_sub_i32 s25, s25, s35
	v_mfma_f32_16x16x32_bf16 v[104:107], v[150:153], v[222:225], 0
	v_mfma_f32_16x16x32_bf16 v[104:107], v[174:177], v[230:233], v[104:107]
	s_add_i32 s38, s34, 1
	s_sub_i32 s35, s25, s28
	s_cmp_ge_u32 s25, s28
	s_cselect_b32 s34, s38, s34
	s_cselect_b32 s25, s35, s25
	v_mfma_f32_16x16x32_bf16 v[88:91], v[150:153], v[234:237], 0
	v_mfma_f32_16x16x32_bf16 v[88:91], v[174:177], v[242:245], v[88:91]
	s_add_i32 s35, s34, 1
	s_cmp_ge_u32 s25, s28
	s_cselect_b32 s25, s35, s34
	s_xor_b32 s25, s25, s29
	s_sub_i32 s28, s25, s29
	v_mfma_f32_16x16x32_bf16 v[72:75], v[150:153], v[238:241], 0
	v_mfma_f32_16x16x32_bf16 v[72:75], v[174:177], v[246:249], v[72:75]
	s_mul_i32 s25, s28, s27
	s_sub_i32 s24, s24, s25
	s_add_i32 s66, s26, s24
	s_mov_b32 s100, s66
	s_ashr_i32 s101, s66, 31
	v_mfma_f32_16x16x32_bf16 v[68:71], v[178:181], v[238:241], 0
	v_mfma_f32_16x16x32_bf16 v[68:71], v[182:185], v[246:249], v[68:71]
	s_lshl_b64 s[26:27], s[100:101], 19
	s_add_u32 s26, s40, s26
	s_addc_u32 s27, s41, s27
	s_and_b64 s[34:35], s[8:9], exec
	s_cselect_b32 s34, s27, s5
	v_mfma_f32_16x16x32_bf16 v[84:87], v[178:181], v[234:237], 0
	v_mfma_f32_16x16x32_bf16 v[84:87], v[182:185], v[242:245], v[84:87]
	s_cselect_b32 s35, s26, s4
	s_ashr_i32 s29, s28, 31
	s_lshl_b64 s[100:101], s[28:29], 19
	s_add_u32 s62, s10, s100
	s_addc_u32 s63, s11, s101
	v_mfma_f32_16x16x32_bf16 v[100:103], v[178:181], v[222:225], 0
	v_mfma_f32_16x16x32_bf16 v[100:103], v[182:185], v[230:233], v[100:103]
	s_and_b64 s[100:101], s[8:9], exec
	s_cselect_b32 s29, s63, s83
	s_cselect_b32 s38, s62, s82
	v_mfma_f32_16x16x32_bf16 v[116:119], v[178:181], v[218:221], 0
	v_mfma_f32_16x16x32_bf16 v[116:119], v[182:185], v[226:229], v[116:119]
	s_barrier
	s_setprio 0
	s_add_i32 s24, s1, s77
	v_lshl_add_u64 v[154:155], s[86:87], 0, v[158:159]
	s_mov_b32 m0, s24
	ds_read_b128 v[218:221], v207 offset:16384
	ds_read_b128 v[222:225], v207 offset:18432
	ds_read_b128 v[226:229], v208 offset:16384
	ds_read_b128 v[230:233], v208 offset:18432
	ds_read_b128 v[234:237], v207 offset:20480
	ds_read_b128 v[238:241], v207 offset:22528
	ds_read_b128 v[242:245], v208 offset:20480
	ds_read_b128 v[246:249], v208 offset:22528
	global_load_lds_dwordx4 v[154:155], off
	v_lshl_add_u64 v[250:251], v[154:155], 0, s[14:15]
	s_add_i32 m0, s24, 0x2000
	s_add_i32 s24, s12, s77
	global_load_lds_dwordx4 v[250:251], off
	v_lshl_add_u64 v[250:251], v[154:155], 0, s[16:17]
	s_mov_b32 m0, s24
	s_nop 0
	global_load_lds_dwordx4 v[250:251], off
	v_lshl_add_u64 v[250:251], v[154:155], 0, s[18:19]
	s_add_i32 m0, s24, 0x2000
	s_nop 0
	global_load_lds_dwordx4 v[250:251], off
	s_waitcnt vmcnt(4)
	s_waitcnt lgkmcnt(0)
	s_barrier
	v_mfma_f32_16x16x32_bf16 v[64:67], v[134:137], v[218:221], 0
	v_mfma_f32_16x16x32_bf16 v[64:67], v[138:141], v[226:229], v[64:67]
	v_mfma_f32_16x16x32_bf16 v[48:51], v[134:137], v[222:225], 0
	v_mfma_f32_16x16x32_bf16 v[48:51], v[138:141], v[230:233], v[48:51]
	v_mfma_f32_16x16x32_bf16 v[32:35], v[134:137], v[234:237], 0
	v_mfma_f32_16x16x32_bf16 v[32:35], v[138:141], v[242:245], v[32:35]
	v_mfma_f32_16x16x32_bf16 v[16:19], v[134:137], v[238:241], 0
	v_mfma_f32_16x16x32_bf16 v[16:19], v[138:141], v[246:249], v[16:19]
	v_mfma_f32_16x16x32_bf16 v[12:15], v[142:145], v[238:241], 0
	v_mfma_f32_16x16x32_bf16 v[12:15], v[146:149], v[246:249], v[12:15]
	v_mfma_f32_16x16x32_bf16 v[28:31], v[142:145], v[234:237], 0
	v_mfma_f32_16x16x32_bf16 v[28:31], v[146:149], v[242:245], v[28:31]
	v_mfma_f32_16x16x32_bf16 v[44:47], v[142:145], v[222:225], 0
	v_mfma_f32_16x16x32_bf16 v[44:47], v[146:149], v[230:233], v[44:47]
	v_mfma_f32_16x16x32_bf16 v[60:63], v[142:145], v[218:221], 0
	v_mfma_f32_16x16x32_bf16 v[60:63], v[146:149], v[226:229], v[60:63]
	v_mfma_f32_16x16x32_bf16 v[56:59], v[150:153], v[218:221], 0
	v_mfma_f32_16x16x32_bf16 v[56:59], v[174:177], v[226:229], v[56:59]
	v_mfma_f32_16x16x32_bf16 v[40:43], v[150:153], v[222:225], 0
	v_mfma_f32_16x16x32_bf16 v[40:43], v[174:177], v[230:233], v[40:43]
	v_mfma_f32_16x16x32_bf16 v[24:27], v[150:153], v[234:237], 0
	v_mfma_f32_16x16x32_bf16 v[24:27], v[174:177], v[242:245], v[24:27]
	v_mfma_f32_16x16x32_bf16 v[8:11], v[150:153], v[238:241], 0
	v_mfma_f32_16x16x32_bf16 v[8:11], v[174:177], v[246:249], v[8:11]
	v_mfma_f32_16x16x32_bf16 v[4:7], v[178:181], v[238:241], 0
	v_mfma_f32_16x16x32_bf16 v[4:7], v[182:185], v[246:249], v[4:7]
	v_mfma_f32_16x16x32_bf16 v[20:23], v[178:181], v[234:237], 0
	v_mfma_f32_16x16x32_bf16 v[20:23], v[182:185], v[242:245], v[20:23]
	v_mfma_f32_16x16x32_bf16 v[36:39], v[178:181], v[222:225], 0
	v_mfma_f32_16x16x32_bf16 v[36:39], v[182:185], v[230:233], v[36:39]
	v_mfma_f32_16x16x32_bf16 v[52:55], v[178:181], v[218:221], 0
	v_mfma_f32_16x16x32_bf16 v[52:55], v[182:185], v[226:229], v[52:55]
	s_barrier
	ds_read_b128 v[134:137], v213
	ds_read_b128 v[138:141], v214
	ds_read_b128 v[142:145], v209
	ds_read_b128 v[146:149], v210
	ds_read_b128 v[150:153], v215
	ds_read_b128 v[174:177], v216
	ds_read_b128 v[178:181], v211
	ds_read_b128 v[182:185], v212
	s_mov_b32 m0, s79
	v_lshl_add_u64 v[250:251], s[82:83], 0, v[0:1]
	ds_read_b128 v[218:221], v207 offset:32768
	ds_read_b128 v[222:225], v207 offset:34816
	ds_read_b128 v[226:229], v208 offset:32768
	ds_read_b128 v[230:233], v208 offset:34816
	ds_read_b128 v[234:237], v207 offset:36864
	ds_read_b128 v[238:241], v207 offset:38912
	ds_read_b128 v[242:245], v208 offset:36864
	ds_read_b128 v[246:249], v208 offset:38912
	global_load_lds_dwordx4 v[250:251], off
	v_lshl_add_u64 v[252:253], v[250:251], 0, s[20:21]
	s_mov_b32 m0, s81
	s_nop 0
	global_load_lds_dwordx4 v[252:253], off
	v_lshl_add_u64 v[252:253], v[250:251], 0, s[14:15]
	s_mov_b32 m0, s97
	v_lshl_add_u64 v[250:251], v[250:251], 0, s[22:23]
	global_load_lds_dwordx4 v[252:253], off
	s_mov_b32 m0, s64
	s_nop 0
	global_load_lds_dwordx4 v[250:251], off
	s_waitcnt vmcnt(8)
	s_waitcnt lgkmcnt(0)
	s_barrier
	v_mfma_f32_16x16x32_bf16 v[128:131], v[134:137], v[218:221], v[128:131]
	v_mfma_f32_16x16x32_bf16 v[128:131], v[138:141], v[226:229], v[128:131]
	v_mfma_f32_16x16x32_bf16 v[112:115], v[138:141], v[230:233], v[112:115]
	v_mfma_f32_16x16x32_bf16 v[112:115], v[134:137], v[222:225], v[112:115]
	v_mfma_f32_16x16x32_bf16 v[96:99], v[134:137], v[234:237], v[96:99]
	v_mfma_f32_16x16x32_bf16 v[96:99], v[138:141], v[242:245], v[96:99]
	v_mfma_f32_16x16x32_bf16 v[80:83], v[138:141], v[246:249], v[80:83]
	v_mfma_f32_16x16x32_bf16 v[80:83], v[134:137], v[238:241], v[80:83]
	v_mfma_f32_16x16x32_bf16 v[76:79], v[142:145], v[238:241], v[76:79]
	v_mfma_f32_16x16x32_bf16 v[76:79], v[146:149], v[246:249], v[76:79]
	v_mfma_f32_16x16x32_bf16 v[92:95], v[146:149], v[242:245], v[92:95]
	v_mfma_f32_16x16x32_bf16 v[92:95], v[142:145], v[234:237], v[92:95]
	v_mfma_f32_16x16x32_bf16 v[108:111], v[142:145], v[222:225], v[108:111]
	v_mfma_f32_16x16x32_bf16 v[108:111], v[146:149], v[230:233], v[108:111]
	v_mfma_f32_16x16x32_bf16 v[124:127], v[146:149], v[226:229], v[124:127]
	v_mfma_f32_16x16x32_bf16 v[124:127], v[142:145], v[218:221], v[124:127]
	v_mfma_f32_16x16x32_bf16 v[120:123], v[150:153], v[218:221], v[120:123]
	v_mfma_f32_16x16x32_bf16 v[120:123], v[174:177], v[226:229], v[120:123]
	v_mfma_f32_16x16x32_bf16 v[104:107], v[174:177], v[230:233], v[104:107]
	v_mfma_f32_16x16x32_bf16 v[104:107], v[150:153], v[222:225], v[104:107]
	v_mfma_f32_16x16x32_bf16 v[88:91], v[150:153], v[234:237], v[88:91]
	v_mfma_f32_16x16x32_bf16 v[88:91], v[174:177], v[242:245], v[88:91]
	v_mfma_f32_16x16x32_bf16 v[72:75], v[174:177], v[246:249], v[72:75]
	v_mfma_f32_16x16x32_bf16 v[72:75], v[150:153], v[238:241], v[72:75]
	v_mfma_f32_16x16x32_bf16 v[68:71], v[178:181], v[238:241], v[68:71]
	v_mfma_f32_16x16x32_bf16 v[68:71], v[182:185], v[246:249], v[68:71]
	v_mfma_f32_16x16x32_bf16 v[84:87], v[182:185], v[242:245], v[84:87]
	v_mfma_f32_16x16x32_bf16 v[84:87], v[178:181], v[234:237], v[84:87]
	v_mfma_f32_16x16x32_bf16 v[100:103], v[178:181], v[222:225], v[100:103]
	v_mfma_f32_16x16x32_bf16 v[100:103], v[182:185], v[230:233], v[100:103]
	v_mfma_f32_16x16x32_bf16 v[116:119], v[182:185], v[226:229], v[116:119]
	v_mfma_f32_16x16x32_bf16 v[116:119], v[178:181], v[218:221], v[116:119]
	s_barrier
	s_add_i32 s24, s70, s77
	v_lshl_add_u64 v[250:251], v[154:155], 0, s[48:49]
	s_mov_b32 m0, s24
	ds_read_b128 v[218:221], v207 offset:49152
	ds_read_b128 v[222:225], v207 offset:51200
	ds_read_b128 v[226:229], v208 offset:49152
	ds_read_b128 v[230:233], v208 offset:51200
	ds_read_b128 v[234:237], v207 offset:53248
	ds_read_b128 v[238:241], v207 offset:55296
	ds_read_b128 v[242:245], v208 offset:53248
	ds_read_b128 v[246:249], v208 offset:55296
	global_load_lds_dwordx4 v[250:251], off
	v_lshl_add_u64 v[250:251], v[154:155], 0, s[50:51]
	s_add_i32 m0, s24, 0x2000
	s_add_i32 s24, s71, s77
	global_load_lds_dwordx4 v[250:251], off
	v_lshl_add_u64 v[250:251], v[154:155], 0, s[52:53]
	s_mov_b32 m0, s24
	v_lshl_add_u64 v[154:155], v[154:155], 0, s[54:55]
	global_load_lds_dwordx4 v[250:251], off
	s_add_i32 m0, s24, 0x2000
	s_nop 0
	global_load_lds_dwordx4 v[154:155], off
	s_waitcnt vmcnt(4)
	s_waitcnt lgkmcnt(0)
	s_barrier
	v_mfma_f32_16x16x32_bf16 v[64:67], v[134:137], v[218:221], v[64:67]
	v_mfma_f32_16x16x32_bf16 v[64:67], v[138:141], v[226:229], v[64:67]
	v_mfma_f32_16x16x32_bf16 v[48:51], v[138:141], v[230:233], v[48:51]
	v_mfma_f32_16x16x32_bf16 v[48:51], v[134:137], v[222:225], v[48:51]
	v_mfma_f32_16x16x32_bf16 v[32:35], v[134:137], v[234:237], v[32:35]
	v_mfma_f32_16x16x32_bf16 v[32:35], v[138:141], v[242:245], v[32:35]
	v_mfma_f32_16x16x32_bf16 v[16:19], v[138:141], v[246:249], v[16:19]
	v_mfma_f32_16x16x32_bf16 v[16:19], v[134:137], v[238:241], v[16:19]
	v_mfma_f32_16x16x32_bf16 v[12:15], v[142:145], v[238:241], v[12:15]
	v_mfma_f32_16x16x32_bf16 v[12:15], v[146:149], v[246:249], v[12:15]
	v_mfma_f32_16x16x32_bf16 v[28:31], v[146:149], v[242:245], v[28:31]
	v_mfma_f32_16x16x32_bf16 v[28:31], v[142:145], v[234:237], v[28:31]
	v_mfma_f32_16x16x32_bf16 v[44:47], v[142:145], v[222:225], v[44:47]
	v_mfma_f32_16x16x32_bf16 v[44:47], v[146:149], v[230:233], v[44:47]
	v_mfma_f32_16x16x32_bf16 v[60:63], v[146:149], v[226:229], v[60:63]
	v_mfma_f32_16x16x32_bf16 v[60:63], v[142:145], v[218:221], v[60:63]
	v_mfma_f32_16x16x32_bf16 v[56:59], v[150:153], v[218:221], v[56:59]
	v_mfma_f32_16x16x32_bf16 v[56:59], v[174:177], v[226:229], v[56:59]
	v_mfma_f32_16x16x32_bf16 v[40:43], v[174:177], v[230:233], v[40:43]
	v_mfma_f32_16x16x32_bf16 v[40:43], v[150:153], v[222:225], v[40:43]
	v_mfma_f32_16x16x32_bf16 v[24:27], v[150:153], v[234:237], v[24:27]
	v_mfma_f32_16x16x32_bf16 v[24:27], v[174:177], v[242:245], v[24:27]
	v_mfma_f32_16x16x32_bf16 v[8:11], v[174:177], v[246:249], v[8:11]
	v_mfma_f32_16x16x32_bf16 v[8:11], v[150:153], v[238:241], v[8:11]
	v_mfma_f32_16x16x32_bf16 v[4:7], v[178:181], v[238:241], v[4:7]
	v_mfma_f32_16x16x32_bf16 v[4:7], v[182:185], v[246:249], v[4:7]
	v_mfma_f32_16x16x32_bf16 v[20:23], v[182:185], v[242:245], v[20:23]
	v_mfma_f32_16x16x32_bf16 v[20:23], v[178:181], v[234:237], v[20:23]
	v_mfma_f32_16x16x32_bf16 v[36:39], v[178:181], v[222:225], v[36:39]
	v_mfma_f32_16x16x32_bf16 v[36:39], v[182:185], v[230:233], v[36:39]
	v_mfma_f32_16x16x32_bf16 v[52:55], v[182:185], v[226:229], v[52:55]
	v_mfma_f32_16x16x32_bf16 v[52:55], v[178:181], v[218:221], v[52:55]
	s_barrier
	s_add_i32 s94, s94, 2
	s_add_u32 vcc_lo, vcc_lo, 0x100
	s_addc_u32 vcc_hi, vcc_hi, 0
	s_cmp_gt_u32 s94, 13

.LBB0_1134:
	s_ashr_i32 s57, s56, 31
	s_lshl_b64 s[60:61], s[56:57], 19
	s_add_u32 s60, s42, s60
	s_addc_u32 s61, s43, s61
	s_and_b64 s[62:63], s[10:11], exec
	s_cselect_b32 s57, s61, s27
	s_cselect_b32 s79, s60, s26
	s_ashr_i32 s59, s58, 31
	s_lshl_b64 s[62:63], s[58:59], 19
	v_readlane_b32 s70, v254, 7
	v_readlane_b32 s71, v254, 8
	s_add_u32 s62, s70, s62
	s_addc_u32 s63, s71, s63
	s_and_b64 s[70:71], s[10:11], exec
	s_cselect_b32 s59, s63, s69
	s_cselect_b32 s80, s62, s68
	s_add_u32 s81, s68, 0x100
	v_lshl_add_u64 v[138:139], s[26:27], 0, v[132:133]
	s_addc_u32 s82, s69, 0
	s_mov_b32 s83, -2
	s_mov_b64 s[68:69], 0
	ds_read_b128 v[168:171], v145
	ds_read_b128 v[174:177], v146
	ds_read_b128 v[178:181], v147
	ds_read_b128 v[182:185], v148
	ds_read_b128 v[194:197], v149
	ds_read_b128 v[198:201], v150
	ds_read_b128 v[202:205], v151
	ds_read_b128 v[206:209], v152
	s_add_u32 s70, s26, s68
	s_addc_u32 s71, s27, s69
	s_add_u32 s70, s70, 0x100
	s_addc_u32 s71, s71, 0
	s_add_u32 s84, s81, s68
	s_addc_u32 s85, s82, s69
	s_cmpk_eq_i32 s68, 0x700
	s_cselect_b32 s85, s59, s85
	s_cselect_b32 s84, s80, s84
	s_cselect_b32 s71, s57, s71
	s_cselect_b32 s70, s79, s70
	v_lshl_add_u64 v[140:141], v[138:139], 0, s[68:69]
	v_lshl_add_u64 v[242:243], v[140:141], 0, s[22:23]
	s_add_i32 m0, s34, 0x8000
	s_mov_b64 s[86:87], 0x20080
	ds_read_b128 v[210:213], v153
	ds_read_b128 v[214:217], v153 offset:2048
	ds_read_b128 v[218:221], v154
	ds_read_b128 v[222:225], v154 offset:2048
	ds_read_b128 v[226:229], v153 offset:4096
	ds_read_b128 v[230:233], v153 offset:6144
	ds_read_b128 v[234:237], v154 offset:4096
	ds_read_b128 v[238:241], v154 offset:6144
	global_load_lds_dwordx4 v[242:243], off
	v_lshl_add_u64 v[242:243], v[140:141], 0, s[86:87]
	s_add_i32 m0, s34, 0xa000
	s_mov_b64 s[86:87], 0x60080
	global_load_lds_dwordx4 v[242:243], off
	v_lshl_add_u64 v[242:243], v[140:141], 0, s[24:25]
	s_add_i32 m0, s34, 0xc000
	v_lshl_add_u64 v[140:141], v[140:141], 0, s[86:87]
	global_load_lds_dwordx4 v[242:243], off
	s_add_i32 m0, s34, 0xe000
	s_nop 0
	global_load_lds_dwordx4 v[140:141], off
	s_waitcnt lgkmcnt(0)
	s_barrier
	v_mfma_f32_16x16x32_bf16 v[128:131], v[168:171], v[210:213], 0
	v_mfma_f32_16x16x32_bf16 v[128:131], v[174:177], v[218:221], v[128:131]
	v_mfma_f32_16x16x32_bf16 v[112:115], v[168:171], v[214:217], 0
	v_mfma_f32_16x16x32_bf16 v[112:115], v[174:177], v[222:225], v[112:115]
	v_mfma_f32_16x16x32_bf16 v[96:99], v[168:171], v[226:229], 0
	v_mfma_f32_16x16x32_bf16 v[96:99], v[174:177], v[234:237], v[96:99]
	v_mfma_f32_16x16x32_bf16 v[80:83], v[168:171], v[230:233], 0
	v_mfma_f32_16x16x32_bf16 v[80:83], v[174:177], v[238:241], v[80:83]
	v_mfma_f32_16x16x32_bf16 v[76:79], v[178:181], v[230:233], 0
	v_mfma_f32_16x16x32_bf16 v[76:79], v[182:185], v[238:241], v[76:79]
	v_mfma_f32_16x16x32_bf16 v[92:95], v[178:181], v[226:229], 0
	v_mfma_f32_16x16x32_bf16 v[92:95], v[182:185], v[234:237], v[92:95]
	v_mfma_f32_16x16x32_bf16 v[108:111], v[178:181], v[214:217], 0
	v_mfma_f32_16x16x32_bf16 v[108:111], v[182:185], v[222:225], v[108:111]
	v_mfma_f32_16x16x32_bf16 v[124:127], v[178:181], v[210:213], 0
	v_mfma_f32_16x16x32_bf16 v[124:127], v[182:185], v[218:221], v[124:127]
	v_mfma_f32_16x16x32_bf16 v[120:123], v[194:197], v[210:213], 0
	v_mfma_f32_16x16x32_bf16 v[120:123], v[198:201], v[218:221], v[120:123]
	v_mfma_f32_16x16x32_bf16 v[104:107], v[194:197], v[214:217], 0
	v_mfma_f32_16x16x32_bf16 v[104:107], v[198:201], v[222:225], v[104:107]
	v_mfma_f32_16x16x32_bf16 v[88:91], v[194:197], v[226:229], 0
	v_mfma_f32_16x16x32_bf16 v[88:91], v[198:201], v[234:237], v[88:91]
	v_mfma_f32_16x16x32_bf16 v[72:75], v[194:197], v[230:233], 0
	v_mfma_f32_16x16x32_bf16 v[72:75], v[198:201], v[238:241], v[72:75]
	v_mfma_f32_16x16x32_bf16 v[68:71], v[202:205], v[230:233], 0
	v_mfma_f32_16x16x32_bf16 v[68:71], v[206:209], v[238:241], v[68:71]
	v_mfma_f32_16x16x32_bf16 v[84:87], v[202:205], v[226:229], 0
	v_mfma_f32_16x16x32_bf16 v[84:87], v[206:209], v[234:237], v[84:87]
	v_mfma_f32_16x16x32_bf16 v[100:103], v[202:205], v[214:217], 0
	v_mfma_f32_16x16x32_bf16 v[100:103], v[206:209], v[222:225], v[100:103]
	v_mfma_f32_16x16x32_bf16 v[116:119], v[202:205], v[210:213], 0
	v_mfma_f32_16x16x32_bf16 v[116:119], v[206:209], v[218:221], v[116:119]
	s_barrier
	s_setprio 0
	v_lshl_add_u64 v[140:141], s[84:85], 0, v[158:159]
	s_add_i32 s84, s67, s3
	s_mov_b32 m0, s84
	ds_read_b128 v[210:213], v153 offset:16384
	ds_read_b128 v[214:217], v153 offset:18432
	ds_read_b128 v[218:221], v154 offset:16384
	ds_read_b128 v[222:225], v154 offset:18432
	ds_read_b128 v[226:229], v153 offset:20480
	ds_read_b128 v[230:233], v153 offset:22528
	ds_read_b128 v[234:237], v154 offset:20480
	ds_read_b128 v[238:241], v154 offset:22528
	global_load_lds_dwordx4 v[140:141], off
	v_lshl_add_u64 v[242:243], v[140:141], 0, s[0:1]
	s_add_i32 m0, s84, 0x2000
	s_add_i32 s84, s72, s3
	global_load_lds_dwordx4 v[242:243], off
	v_lshl_add_u64 v[242:243], v[140:141], 0, s[12:13]
	s_mov_b32 m0, s84
	s_nop 0
	global_load_lds_dwordx4 v[242:243], off
	v_lshl_add_u64 v[242:243], v[140:141], 0, s[14:15]
	s_add_i32 m0, s84, 0x2000
	s_nop 0
	global_load_lds_dwordx4 v[242:243], off
	s_waitcnt vmcnt(4)
	s_waitcnt lgkmcnt(0)
	s_barrier
	v_mfma_f32_16x16x32_bf16 v[64:67], v[168:171], v[210:213], 0
	v_mfma_f32_16x16x32_bf16 v[64:67], v[174:177], v[218:221], v[64:67]
	v_mfma_f32_16x16x32_bf16 v[48:51], v[168:171], v[214:217], 0
	v_mfma_f32_16x16x32_bf16 v[48:51], v[174:177], v[222:225], v[48:51]
	v_mfma_f32_16x16x32_bf16 v[32:35], v[168:171], v[226:229], 0
	v_mfma_f32_16x16x32_bf16 v[32:35], v[174:177], v[234:237], v[32:35]
	v_mfma_f32_16x16x32_bf16 v[16:19], v[168:171], v[230:233], 0
	v_mfma_f32_16x16x32_bf16 v[16:19], v[174:177], v[238:241], v[16:19]
	v_mfma_f32_16x16x32_bf16 v[12:15], v[178:181], v[230:233], 0
	v_mfma_f32_16x16x32_bf16 v[12:15], v[182:185], v[238:241], v[12:15]
	v_mfma_f32_16x16x32_bf16 v[28:31], v[178:181], v[226:229], 0
	v_mfma_f32_16x16x32_bf16 v[28:31], v[182:185], v[234:237], v[28:31]
	v_mfma_f32_16x16x32_bf16 v[44:47], v[178:181], v[214:217], 0
	v_mfma_f32_16x16x32_bf16 v[44:47], v[182:185], v[222:225], v[44:47]
	v_mfma_f32_16x16x32_bf16 v[60:63], v[178:181], v[210:213], 0
	v_mfma_f32_16x16x32_bf16 v[60:63], v[182:185], v[218:221], v[60:63]
	v_mfma_f32_16x16x32_bf16 v[56:59], v[194:197], v[210:213], 0
	v_mfma_f32_16x16x32_bf16 v[56:59], v[198:201], v[218:221], v[56:59]
	v_mfma_f32_16x16x32_bf16 v[40:43], v[194:197], v[214:217], 0
	v_mfma_f32_16x16x32_bf16 v[40:43], v[198:201], v[222:225], v[40:43]
	v_mfma_f32_16x16x32_bf16 v[24:27], v[194:197], v[226:229], 0
	v_mfma_f32_16x16x32_bf16 v[24:27], v[198:201], v[234:237], v[24:27]
	v_mfma_f32_16x16x32_bf16 v[8:11], v[194:197], v[230:233], 0
	v_mfma_f32_16x16x32_bf16 v[8:11], v[198:201], v[238:241], v[8:11]
	v_mfma_f32_16x16x32_bf16 v[4:7], v[202:205], v[230:233], 0
	v_mfma_f32_16x16x32_bf16 v[4:7], v[206:209], v[238:241], v[4:7]
	v_mfma_f32_16x16x32_bf16 v[20:23], v[202:205], v[226:229], 0
	v_mfma_f32_16x16x32_bf16 v[20:23], v[206:209], v[234:237], v[20:23]
	v_mfma_f32_16x16x32_bf16 v[36:39], v[202:205], v[214:217], 0
	v_mfma_f32_16x16x32_bf16 v[36:39], v[206:209], v[222:225], v[36:39]
	v_mfma_f32_16x16x32_bf16 v[52:55], v[202:205], v[210:213], 0
	v_mfma_f32_16x16x32_bf16 v[52:55], v[206:209], v[218:221], v[52:55]
	s_barrier
	ds_read_b128 v[168:171], v163
	ds_read_b128 v[174:177], v164
	ds_read_b128 v[178:181], v155
	ds_read_b128 v[182:185], v160
	ds_read_b128 v[194:197], v165
	ds_read_b128 v[198:201], v166
	ds_read_b128 v[202:205], v161
	ds_read_b128 v[206:209], v162
	s_mov_b32 m0, s34
	v_lshl_add_u64 v[242:243], s[70:71], 0, v[0:1]
	ds_read_b128 v[210:213], v153 offset:32768
	ds_read_b128 v[214:217], v153 offset:34816
	ds_read_b128 v[218:221], v154 offset:32768
	ds_read_b128 v[222:225], v154 offset:34816
	ds_read_b128 v[226:229], v153 offset:36864
	ds_read_b128 v[230:233], v153 offset:38912
	ds_read_b128 v[234:237], v154 offset:36864
	ds_read_b128 v[238:241], v154 offset:38912
	global_load_lds_dwordx4 v[242:243], off
	v_lshl_add_u64 v[244:245], v[242:243], 0, s[16:17]
	s_mov_b32 m0, s35
	s_nop 0
	global_load_lds_dwordx4 v[244:245], off
	v_lshl_add_u64 v[244:245], v[242:243], 0, s[0:1]
	s_mov_b32 m0, s38
	v_lshl_add_u64 v[242:243], v[242:243], 0, s[18:19]
	global_load_lds_dwordx4 v[244:245], off
	s_mov_b32 m0, s39
	s_nop 0
	global_load_lds_dwordx4 v[242:243], off
	s_waitcnt vmcnt(8)
	s_waitcnt lgkmcnt(0)
	s_barrier
	v_mfma_f32_16x16x32_bf16 v[128:131], v[168:171], v[210:213], v[128:131]
	v_mfma_f32_16x16x32_bf16 v[128:131], v[174:177], v[218:221], v[128:131]
	v_mfma_f32_16x16x32_bf16 v[112:115], v[174:177], v[222:225], v[112:115]
	v_mfma_f32_16x16x32_bf16 v[112:115], v[168:171], v[214:217], v[112:115]
	v_mfma_f32_16x16x32_bf16 v[96:99], v[168:171], v[226:229], v[96:99]
	v_mfma_f32_16x16x32_bf16 v[96:99], v[174:177], v[234:237], v[96:99]
	v_mfma_f32_16x16x32_bf16 v[80:83], v[174:177], v[238:241], v[80:83]
	v_mfma_f32_16x16x32_bf16 v[80:83], v[168:171], v[230:233], v[80:83]
	v_mfma_f32_16x16x32_bf16 v[76:79], v[178:181], v[230:233], v[76:79]
	v_mfma_f32_16x16x32_bf16 v[76:79], v[182:185], v[238:241], v[76:79]
	v_mfma_f32_16x16x32_bf16 v[92:95], v[182:185], v[234:237], v[92:95]
	v_mfma_f32_16x16x32_bf16 v[92:95], v[178:181], v[226:229], v[92:95]
	v_mfma_f32_16x16x32_bf16 v[108:111], v[178:181], v[214:217], v[108:111]
	v_mfma_f32_16x16x32_bf16 v[108:111], v[182:185], v[222:225], v[108:111]
	v_mfma_f32_16x16x32_bf16 v[124:127], v[182:185], v[218:221], v[124:127]
	v_mfma_f32_16x16x32_bf16 v[124:127], v[178:181], v[210:213], v[124:127]
	v_mfma_f32_16x16x32_bf16 v[120:123], v[194:197], v[210:213], v[120:123]
	v_mfma_f32_16x16x32_bf16 v[120:123], v[198:201], v[218:221], v[120:123]
	v_mfma_f32_16x16x32_bf16 v[104:107], v[198:201], v[222:225], v[104:107]
	v_mfma_f32_16x16x32_bf16 v[104:107], v[194:197], v[214:217], v[104:107]
	v_mfma_f32_16x16x32_bf16 v[88:91], v[194:197], v[226:229], v[88:91]
	v_mfma_f32_16x16x32_bf16 v[88:91], v[198:201], v[234:237], v[88:91]
	v_mfma_f32_16x16x32_bf16 v[72:75], v[198:201], v[238:241], v[72:75]
	v_mfma_f32_16x16x32_bf16 v[72:75], v[194:197], v[230:233], v[72:75]
	v_mfma_f32_16x16x32_bf16 v[68:71], v[202:205], v[230:233], v[68:71]
	v_mfma_f32_16x16x32_bf16 v[68:71], v[206:209], v[238:241], v[68:71]
	v_mfma_f32_16x16x32_bf16 v[84:87], v[206:209], v[234:237], v[84:87]
	v_mfma_f32_16x16x32_bf16 v[84:87], v[202:205], v[226:229], v[84:87]
	v_mfma_f32_16x16x32_bf16 v[100:103], v[202:205], v[214:217], v[100:103]
	v_mfma_f32_16x16x32_bf16 v[100:103], v[206:209], v[222:225], v[100:103]
	v_mfma_f32_16x16x32_bf16 v[116:119], v[206:209], v[218:221], v[116:119]
	v_mfma_f32_16x16x32_bf16 v[116:119], v[202:205], v[210:213], v[116:119]
	s_barrier
	s_add_i32 s70, s73, s3
	v_lshl_add_u64 v[242:243], v[140:141], 0, s[22:23]
	s_mov_b32 m0, s70
	ds_read_b128 v[210:213], v153 offset:49152
	ds_read_b128 v[214:217], v153 offset:51200
	ds_read_b128 v[218:221], v154 offset:49152
	ds_read_b128 v[222:225], v154 offset:51200
	ds_read_b128 v[226:229], v153 offset:53248
	ds_read_b128 v[230:233], v153 offset:55296
	ds_read_b128 v[234:237], v154 offset:53248
	ds_read_b128 v[238:241], v154 offset:55296
	global_load_lds_dwordx4 v[242:243], off
	v_lshl_add_u64 v[242:243], v[140:141], 0, s[24:25]
	s_add_i32 m0, s70, 0x2000
	s_add_i32 s70, s77, s3
	global_load_lds_dwordx4 v[242:243], off
	v_lshl_add_u64 v[242:243], v[140:141], 0, s[28:29]
	s_mov_b32 m0, s70
	v_lshl_add_u64 v[140:141], v[140:141], 0, s[36:37]
	global_load_lds_dwordx4 v[242:243], off
	s_add_i32 m0, s70, 0x2000
	s_nop 0
	global_load_lds_dwordx4 v[140:141], off
	s_waitcnt vmcnt(4)
	s_waitcnt lgkmcnt(0)
	s_barrier
	v_mfma_f32_16x16x32_bf16 v[64:67], v[168:171], v[210:213], v[64:67]
	v_mfma_f32_16x16x32_bf16 v[64:67], v[174:177], v[218:221], v[64:67]
	v_mfma_f32_16x16x32_bf16 v[48:51], v[174:177], v[222:225], v[48:51]
	v_mfma_f32_16x16x32_bf16 v[48:51], v[168:171], v[214:217], v[48:51]
	v_mfma_f32_16x16x32_bf16 v[32:35], v[168:171], v[226:229], v[32:35]
	v_mfma_f32_16x16x32_bf16 v[32:35], v[174:177], v[234:237], v[32:35]
	v_mfma_f32_16x16x32_bf16 v[16:19], v[174:177], v[238:241], v[16:19]
	v_mfma_f32_16x16x32_bf16 v[16:19], v[168:171], v[230:233], v[16:19]
	v_mfma_f32_16x16x32_bf16 v[12:15], v[178:181], v[230:233], v[12:15]
	v_mfma_f32_16x16x32_bf16 v[12:15], v[182:185], v[238:241], v[12:15]
	v_mfma_f32_16x16x32_bf16 v[28:31], v[182:185], v[234:237], v[28:31]
	v_mfma_f32_16x16x32_bf16 v[28:31], v[178:181], v[226:229], v[28:31]
	v_mfma_f32_16x16x32_bf16 v[44:47], v[178:181], v[214:217], v[44:47]
	v_mfma_f32_16x16x32_bf16 v[44:47], v[182:185], v[222:225], v[44:47]
	v_mfma_f32_16x16x32_bf16 v[60:63], v[182:185], v[218:221], v[60:63]
	v_mfma_f32_16x16x32_bf16 v[60:63], v[178:181], v[210:213], v[60:63]
	v_mfma_f32_16x16x32_bf16 v[56:59], v[194:197], v[210:213], v[56:59]
	v_mfma_f32_16x16x32_bf16 v[56:59], v[198:201], v[218:221], v[56:59]
	v_mfma_f32_16x16x32_bf16 v[40:43], v[198:201], v[222:225], v[40:43]
	v_mfma_f32_16x16x32_bf16 v[40:43], v[194:197], v[214:217], v[40:43]
	v_mfma_f32_16x16x32_bf16 v[24:27], v[194:197], v[226:229], v[24:27]
	v_mfma_f32_16x16x32_bf16 v[24:27], v[198:201], v[234:237], v[24:27]
	v_mfma_f32_16x16x32_bf16 v[8:11], v[198:201], v[238:241], v[8:11]
	v_mfma_f32_16x16x32_bf16 v[8:11], v[194:197], v[230:233], v[8:11]
	v_mfma_f32_16x16x32_bf16 v[4:7], v[202:205], v[230:233], v[4:7]
	v_mfma_f32_16x16x32_bf16 v[4:7], v[206:209], v[238:241], v[4:7]
	v_mfma_f32_16x16x32_bf16 v[20:23], v[206:209], v[234:237], v[20:23]
	v_mfma_f32_16x16x32_bf16 v[20:23], v[202:205], v[226:229], v[20:23]
	v_mfma_f32_16x16x32_bf16 v[36:39], v[202:205], v[214:217], v[36:39]
	v_mfma_f32_16x16x32_bf16 v[36:39], v[206:209], v[222:225], v[36:39]
	v_mfma_f32_16x16x32_bf16 v[52:55], v[206:209], v[218:221], v[52:55]
	v_mfma_f32_16x16x32_bf16 v[52:55], v[202:205], v[210:213], v[52:55]
	s_barrier
	s_add_i32 s83, s83, 2
	s_add_u32 s68, s68, 0x100
	s_addc_u32 s69, s69, 0
	s_cmp_gt_u32 s83, 13
